# scan16 counted LDS waits made independent of ds_write / ds_read_b32 completion order
# baseline (speedup 1.0000x reference)
.LBB0_1632:
	s_andn2_b64 vcc, exec, s[34:35]
	s_movk_i32 s2, 0x700
	s_cbranch_vccnz .LBB0_1634
	s_movk_i32 s2, 0xf00
	v_add_f32_dpp v234, v63, v63 quad_perm:[1,0,3,2] row_mask:0xf bank_mask:0xf bound_ctrl:1
	v_mov_b32_e32 v240, v53
	s_nop 0
	v_add_f32_dpp v234, v234, v234 quad_perm:[2,3,0,1] row_mask:0xf bank_mask:0xf bound_ctrl:1
	s_nop 1
	v_add_f32_dpp v234, v234, v234 row_half_mirror row_mask:0xf bank_mask:0xf bound_ctrl:1
	s_nop 1
	v_add_f32_dpp v234, v234, v234 row_mirror row_mask:0xf bank_mask:0xf bound_ctrl:1
	v_pk_fma_f32 v[36:37], v[32:33], v[234:235], v[54:55] op_sel_hi:[1,0,1]
	v_pk_fma_f32 v[34:35], v[30:31], v[234:235], v[56:57] op_sel_hi:[1,0,1]
	ds_read_b128 v[224:227], v51 offset:3840
	s_waitcnt lgkmcnt(5)
	v_pk_mul_f32 v[232:233], v[28:29], v[36:37]
	v_pk_fma_f32 v[232:233], v[26:27], v[34:35], v[232:233]
	ds_read_b128 v[64:67], v51 offset:3328
	ds_read_b128 v[68:71], v51 offset:3584
	v_add_f32_e32 v234, v232, v233
	v_pk_mul_f32 v[236:237], v[24:25], v[36:37]
	v_pk_fma_f32 v[236:237], v[22:23], v[34:35], v[236:237]
	v_add_f32_dpp v234, v234, v234 quad_perm:[1,0,3,2] row_mask:0xf bank_mask:0xf bound_ctrl:1
	s_waitcnt lgkmcnt(5)
	v_pk_mul_f32 v[228:229], v[18:19], v[34:35]
	v_add_f32_e32 v238, v236, v237
	v_add_f32_dpp v234, v234, v234 quad_perm:[2,3,0,1] row_mask:0xf bank_mask:0xf bound_ctrl:1
	v_pk_mul_f32 v[230:231], v[20:21], v[36:37]
	v_pk_fma_f32 v[56:57], v[14:15], v[240:241], v[228:229] op_sel_hi:[1,0,1]
	v_add_f32_dpp v234, v234, v234 row_half_mirror row_mask:0xf bank_mask:0xf bound_ctrl:1
	v_pk_fma_f32 v[54:55], v[16:17], v[240:241], v[230:231] op_sel_hi:[1,0,1]
	v_add_f32_dpp v238, v238, v238 quad_perm:[1,0,3,2] row_mask:0xf bank_mask:0xf bound_ctrl:1
	v_add_f32_dpp v234, v234, v234 row_mirror row_mask:0xf bank_mask:0xf bound_ctrl:1
	ds_read_b32 v242, v62 offset:4352
	ds_read_b128 v[30:33], v51 offset:4096
	ds_read_b128 v[22:25], v51 offset:3072
	s_waitcnt lgkmcnt(6)
	v_pk_fma_f32 v[36:37], v[12:13], v[234:235], v[54:55] op_sel_hi:[1,0,1]
	v_pk_fma_f32 v[34:35], v[10:11], v[234:235], v[56:57] op_sel_hi:[1,0,1]
	v_add_f32_dpp v238, v238, v238 quad_perm:[2,3,0,1] row_mask:0xf bank_mask:0xf bound_ctrl:1
	ds_write_b32 v49, v238
	ds_read_b128 v[26:29], v51 offset:5376
	s_waitcnt lgkmcnt(5)
	v_pk_mul_f32 v[232:233], v[226:227], v[36:37]
	v_pk_fma_f32 v[232:233], v[224:225], v[34:35], v[232:233]
	ds_read_b128 v[18:21], v51 offset:4864
	ds_read_b128 v[14:17], v51 offset:5120
	v_add_f32_e32 v234, v232, v233
	v_pk_mul_f32 v[236:237], v[8:9], v[36:37]
	v_pk_fma_f32 v[236:237], v[6:7], v[34:35], v[236:237]
	v_add_f32_dpp v234, v234, v234 quad_perm:[1,0,3,2] row_mask:0xf bank_mask:0xf bound_ctrl:1
	s_waitcnt lgkmcnt(5)
	v_pk_mul_f32 v[228:229], v[64:65], v[34:35]
	v_add_f32_e32 v238, v236, v237
	v_add_f32_dpp v234, v234, v234 quad_perm:[2,3,0,1] row_mask:0xf bank_mask:0xf bound_ctrl:1
	v_pk_mul_f32 v[230:231], v[66:67], v[36:37]
	v_pk_fma_f32 v[56:57], v[68:69], v[242:243], v[228:229] op_sel_hi:[1,0,1]
	v_add_f32_dpp v234, v234, v234 row_half_mirror row_mask:0xf bank_mask:0xf bound_ctrl:1
	v_pk_fma_f32 v[54:55], v[70:71], v[242:243], v[230:231] op_sel_hi:[1,0,1]
	v_add_f32_dpp v238, v238, v238 quad_perm:[1,0,3,2] row_mask:0xf bank_mask:0xf bound_ctrl:1
	v_add_f32_dpp v234, v234, v234 row_mirror row_mask:0xf bank_mask:0xf bound_ctrl:1
	ds_read_b32 v240, v62 offset:5888
	ds_read_b128 v[10:13], v51 offset:5632
	ds_read_b128 v[6:9], v51 offset:4608
	s_waitcnt lgkmcnt(6)
	v_pk_fma_f32 v[36:37], v[32:33], v[234:235], v[54:55] op_sel_hi:[1,0,1]
	v_pk_fma_f32 v[34:35], v[30:31], v[234:235], v[56:57] op_sel_hi:[1,0,1]
	v_add_f32_dpp v238, v238, v238 quad_perm:[2,3,0,1] row_mask:0xf bank_mask:0xf bound_ctrl:1
	ds_write_b32 v49, v238 offset:256
	ds_read_b128 v[224:227], v51 offset:6912
	s_waitcnt lgkmcnt(5)
	v_pk_mul_f32 v[232:233], v[28:29], v[36:37]
	v_pk_fma_f32 v[232:233], v[26:27], v[34:35], v[232:233]
	ds_read_b128 v[64:67], v51 offset:6400
	ds_read_b128 v[68:71], v51 offset:6656
	v_add_f32_e32 v234, v232, v233
	v_pk_mul_f32 v[236:237], v[24:25], v[36:37]
	v_pk_fma_f32 v[236:237], v[22:23], v[34:35], v[236:237]
	v_add_f32_dpp v234, v234, v234 quad_perm:[1,0,3,2] row_mask:0xf bank_mask:0xf bound_ctrl:1
	s_waitcnt lgkmcnt(5)
	v_pk_mul_f32 v[228:229], v[18:19], v[34:35]
	v_add_f32_e32 v238, v236, v237
	v_add_f32_dpp v234, v234, v234 quad_perm:[2,3,0,1] row_mask:0xf bank_mask:0xf bound_ctrl:1
	v_pk_mul_f32 v[230:231], v[20:21], v[36:37]
	v_pk_fma_f32 v[56:57], v[14:15], v[240:241], v[228:229] op_sel_hi:[1,0,1]
	v_add_f32_dpp v234, v234, v234 row_half_mirror row_mask:0xf bank_mask:0xf bound_ctrl:1
	v_pk_fma_f32 v[54:55], v[16:17], v[240:241], v[230:231] op_sel_hi:[1,0,1]
	v_add_f32_dpp v238, v238, v238 quad_perm:[1,0,3,2] row_mask:0xf bank_mask:0xf bound_ctrl:1
	v_add_f32_dpp v234, v234, v234 row_mirror row_mask:0xf bank_mask:0xf bound_ctrl:1
	ds_read_b32 v242, v62 offset:7424
	ds_read_b128 v[30:33], v51 offset:7168
	ds_read_b128 v[22:25], v51 offset:6144
	s_waitcnt lgkmcnt(6)
	v_pk_fma_f32 v[36:37], v[12:13], v[234:235], v[54:55] op_sel_hi:[1,0,1]
	v_pk_fma_f32 v[34:35], v[10:11], v[234:235], v[56:57] op_sel_hi:[1,0,1]
	v_add_f32_dpp v238, v238, v238 quad_perm:[2,3,0,1] row_mask:0xf bank_mask:0xf bound_ctrl:1
	ds_write_b32 v49, v238 offset:512
	ds_read_b128 v[26:29], v51 offset:8448
	s_waitcnt lgkmcnt(5)
	v_pk_mul_f32 v[232:233], v[226:227], v[36:37]
	v_pk_fma_f32 v[232:233], v[224:225], v[34:35], v[232:233]
	ds_read_b128 v[18:21], v51 offset:7936
	ds_read_b128 v[14:17], v51 offset:8192
	v_add_f32_e32 v234, v232, v233
	v_pk_mul_f32 v[236:237], v[8:9], v[36:37]
	v_pk_fma_f32 v[236:237], v[6:7], v[34:35], v[236:237]
	v_add_f32_dpp v234, v234, v234 quad_perm:[1,0,3,2] row_mask:0xf bank_mask:0xf bound_ctrl:1
	s_waitcnt lgkmcnt(5)
	v_pk_mul_f32 v[228:229], v[64:65], v[34:35]
	v_add_f32_e32 v238, v236, v237
	v_add_f32_dpp v234, v234, v234 quad_perm:[2,3,0,1] row_mask:0xf bank_mask:0xf bound_ctrl:1
	v_pk_mul_f32 v[230:231], v[66:67], v[36:37]
	v_pk_fma_f32 v[56:57], v[68:69], v[242:243], v[228:229] op_sel_hi:[1,0,1]
	v_add_f32_dpp v234, v234, v234 row_half_mirror row_mask:0xf bank_mask:0xf bound_ctrl:1
	v_pk_fma_f32 v[54:55], v[70:71], v[242:243], v[230:231] op_sel_hi:[1,0,1]
	v_add_f32_dpp v238, v238, v238 quad_perm:[1,0,3,2] row_mask:0xf bank_mask:0xf bound_ctrl:1
	v_add_f32_dpp v234, v234, v234 row_mirror row_mask:0xf bank_mask:0xf bound_ctrl:1
	ds_read_b32 v240, v62 offset:8960
	ds_read_b128 v[10:13], v51 offset:8704
	ds_read_b128 v[6:9], v51 offset:7680
	s_waitcnt lgkmcnt(6)
	v_pk_fma_f32 v[36:37], v[32:33], v[234:235], v[54:55] op_sel_hi:[1,0,1]
	v_pk_fma_f32 v[34:35], v[30:31], v[234:235], v[56:57] op_sel_hi:[1,0,1]
	v_add_f32_dpp v238, v238, v238 quad_perm:[2,3,0,1] row_mask:0xf bank_mask:0xf bound_ctrl:1
	ds_write_b32 v49, v238 offset:768
	ds_read_b128 v[224:227], v51 offset:9984
	s_waitcnt lgkmcnt(5)
	v_pk_mul_f32 v[232:233], v[28:29], v[36:37]
	v_pk_fma_f32 v[232:233], v[26:27], v[34:35], v[232:233]
	ds_read_b128 v[64:67], v51 offset:9472
	ds_read_b128 v[68:71], v51 offset:9728
	v_add_f32_e32 v234, v232, v233
	v_pk_mul_f32 v[236:237], v[24:25], v[36:37]
	v_pk_fma_f32 v[236:237], v[22:23], v[34:35], v[236:237]
	v_add_f32_dpp v234, v234, v234 quad_perm:[1,0,3,2] row_mask:0xf bank_mask:0xf bound_ctrl:1
	s_waitcnt lgkmcnt(5)
	v_pk_mul_f32 v[228:229], v[18:19], v[34:35]
	v_add_f32_e32 v238, v236, v237
	v_add_f32_dpp v234, v234, v234 quad_perm:[2,3,0,1] row_mask:0xf bank_mask:0xf bound_ctrl:1
	v_pk_mul_f32 v[230:231], v[20:21], v[36:37]
	v_pk_fma_f32 v[56:57], v[14:15], v[240:241], v[228:229] op_sel_hi:[1,0,1]
	v_add_f32_dpp v234, v234, v234 row_half_mirror row_mask:0xf bank_mask:0xf bound_ctrl:1
	v_pk_fma_f32 v[54:55], v[16:17], v[240:241], v[230:231] op_sel_hi:[1,0,1]
	v_add_f32_dpp v238, v238, v238 quad_perm:[1,0,3,2] row_mask:0xf bank_mask:0xf bound_ctrl:1
	v_add_f32_dpp v234, v234, v234 row_mirror row_mask:0xf bank_mask:0xf bound_ctrl:1
	ds_read_b32 v242, v62 offset:10496
	ds_read_b128 v[30:33], v51 offset:10240
	ds_read_b128 v[22:25], v51 offset:9216
	s_waitcnt lgkmcnt(6)
	v_pk_fma_f32 v[36:37], v[12:13], v[234:235], v[54:55] op_sel_hi:[1,0,1]
	v_pk_fma_f32 v[34:35], v[10:11], v[234:235], v[56:57] op_sel_hi:[1,0,1]
	v_add_f32_dpp v238, v238, v238 quad_perm:[2,3,0,1] row_mask:0xf bank_mask:0xf bound_ctrl:1
	ds_write_b32 v49, v238 offset:1024
	ds_read_b128 v[26:29], v51 offset:11520
	s_waitcnt lgkmcnt(5)
	v_pk_mul_f32 v[232:233], v[226:227], v[36:37]
	v_pk_fma_f32 v[232:233], v[224:225], v[34:35], v[232:233]
	ds_read_b128 v[18:21], v51 offset:11008
	ds_read_b128 v[14:17], v51 offset:11264
	v_add_f32_e32 v234, v232, v233
	v_pk_mul_f32 v[236:237], v[8:9], v[36:37]
	v_pk_fma_f32 v[236:237], v[6:7], v[34:35], v[236:237]
	v_add_f32_dpp v234, v234, v234 quad_perm:[1,0,3,2] row_mask:0xf bank_mask:0xf bound_ctrl:1
	s_waitcnt lgkmcnt(5)
	v_pk_mul_f32 v[228:229], v[64:65], v[34:35]
	v_add_f32_e32 v238, v236, v237
	v_add_f32_dpp v234, v234, v234 quad_perm:[2,3,0,1] row_mask:0xf bank_mask:0xf bound_ctrl:1
	v_pk_mul_f32 v[230:231], v[66:67], v[36:37]
	v_pk_fma_f32 v[56:57], v[68:69], v[242:243], v[228:229] op_sel_hi:[1,0,1]
	v_add_f32_dpp v234, v234, v234 row_half_mirror row_mask:0xf bank_mask:0xf bound_ctrl:1
	v_pk_fma_f32 v[54:55], v[70:71], v[242:243], v[230:231] op_sel_hi:[1,0,1]
	v_add_f32_dpp v238, v238, v238 quad_perm:[1,0,3,2] row_mask:0xf bank_mask:0xf bound_ctrl:1
	v_add_f32_dpp v234, v234, v234 row_mirror row_mask:0xf bank_mask:0xf bound_ctrl:1
	ds_read_b32 v240, v62 offset:12032
	ds_read_b128 v[10:13], v51 offset:11776
	ds_read_b128 v[6:9], v51 offset:10752
	s_waitcnt lgkmcnt(6)
	v_pk_fma_f32 v[36:37], v[32:33], v[234:235], v[54:55] op_sel_hi:[1,0,1]
	v_pk_fma_f32 v[34:35], v[30:31], v[234:235], v[56:57] op_sel_hi:[1,0,1]
	v_add_f32_dpp v238, v238, v238 quad_perm:[2,3,0,1] row_mask:0xf bank_mask:0xf bound_ctrl:1
	ds_write_b32 v49, v238 offset:1280
	ds_read_b128 v[224:227], v51 offset:13056
	s_waitcnt lgkmcnt(5)
	v_pk_mul_f32 v[232:233], v[28:29], v[36:37]
	v_pk_fma_f32 v[232:233], v[26:27], v[34:35], v[232:233]
	ds_read_b128 v[64:67], v51 offset:12544
	ds_read_b128 v[68:71], v51 offset:12800
	v_add_f32_e32 v234, v232, v233
	v_pk_mul_f32 v[236:237], v[24:25], v[36:37]
	v_pk_fma_f32 v[236:237], v[22:23], v[34:35], v[236:237]
	v_add_f32_dpp v234, v234, v234 quad_perm:[1,0,3,2] row_mask:0xf bank_mask:0xf bound_ctrl:1
	s_waitcnt lgkmcnt(5)
	v_pk_mul_f32 v[228:229], v[18:19], v[34:35]
	v_add_f32_e32 v238, v236, v237
	v_add_f32_dpp v234, v234, v234 quad_perm:[2,3,0,1] row_mask:0xf bank_mask:0xf bound_ctrl:1
	v_pk_mul_f32 v[230:231], v[20:21], v[36:37]
	v_pk_fma_f32 v[56:57], v[14:15], v[240:241], v[228:229] op_sel_hi:[1,0,1]
	v_add_f32_dpp v234, v234, v234 row_half_mirror row_mask:0xf bank_mask:0xf bound_ctrl:1
	v_pk_fma_f32 v[54:55], v[16:17], v[240:241], v[230:231] op_sel_hi:[1,0,1]
	v_add_f32_dpp v238, v238, v238 quad_perm:[1,0,3,2] row_mask:0xf bank_mask:0xf bound_ctrl:1
	v_add_f32_dpp v234, v234, v234 row_mirror row_mask:0xf bank_mask:0xf bound_ctrl:1
	ds_read_b32 v242, v62 offset:13568
	ds_read_b128 v[30:33], v51 offset:13312
	ds_read_b128 v[22:25], v51 offset:12288
	s_waitcnt lgkmcnt(6)
	v_pk_fma_f32 v[36:37], v[12:13], v[234:235], v[54:55] op_sel_hi:[1,0,1]
	v_pk_fma_f32 v[34:35], v[10:11], v[234:235], v[56:57] op_sel_hi:[1,0,1]
	v_add_f32_dpp v238, v238, v238 quad_perm:[2,3,0,1] row_mask:0xf bank_mask:0xf bound_ctrl:1
	ds_write_b32 v49, v238 offset:1536
	ds_read_b128 v[26:29], v51 offset:14592
	s_waitcnt lgkmcnt(5)
	v_pk_mul_f32 v[232:233], v[226:227], v[36:37]
	v_pk_fma_f32 v[232:233], v[224:225], v[34:35], v[232:233]
	ds_read_b128 v[18:21], v51 offset:14080
	ds_read_b128 v[14:17], v51 offset:14336
	v_add_f32_e32 v234, v232, v233
	v_pk_mul_f32 v[236:237], v[8:9], v[36:37]
	v_pk_fma_f32 v[236:237], v[6:7], v[34:35], v[236:237]
	v_add_f32_dpp v234, v234, v234 quad_perm:[1,0,3,2] row_mask:0xf bank_mask:0xf bound_ctrl:1
	s_waitcnt lgkmcnt(5)
	v_pk_mul_f32 v[228:229], v[64:65], v[34:35]
	v_add_f32_e32 v238, v236, v237
	v_add_f32_dpp v234, v234, v234 quad_perm:[2,3,0,1] row_mask:0xf bank_mask:0xf bound_ctrl:1
	v_pk_mul_f32 v[230:231], v[66:67], v[36:37]
	v_pk_fma_f32 v[56:57], v[68:69], v[242:243], v[228:229] op_sel_hi:[1,0,1]
	v_add_f32_dpp v234, v234, v234 row_half_mirror row_mask:0xf bank_mask:0xf bound_ctrl:1
	v_pk_fma_f32 v[54:55], v[70:71], v[242:243], v[230:231] op_sel_hi:[1,0,1]
	v_add_f32_dpp v238, v238, v238 quad_perm:[1,0,3,2] row_mask:0xf bank_mask:0xf bound_ctrl:1
	v_add_f32_dpp v234, v234, v234 row_mirror row_mask:0xf bank_mask:0xf bound_ctrl:1
	ds_read_b32 v240, v62 offset:15104
	ds_read_b128 v[10:13], v51 offset:14848
	ds_read_b128 v[6:9], v51 offset:13824
	s_waitcnt lgkmcnt(6)
	v_pk_fma_f32 v[36:37], v[32:33], v[234:235], v[54:55] op_sel_hi:[1,0,1]
	v_pk_fma_f32 v[34:35], v[30:31], v[234:235], v[56:57] op_sel_hi:[1,0,1]
	v_add_f32_dpp v238, v238, v238 quad_perm:[2,3,0,1] row_mask:0xf bank_mask:0xf bound_ctrl:1
	ds_write_b32 v49, v238 offset:1792
	ds_read_b128 v[224:227], v51 offset:16128
	s_waitcnt lgkmcnt(5)
	v_pk_mul_f32 v[232:233], v[28:29], v[36:37]
	v_pk_fma_f32 v[232:233], v[26:27], v[34:35], v[232:233]
	ds_read_b128 v[64:67], v51 offset:15616
	ds_read_b128 v[68:71], v51 offset:15872
	v_add_f32_e32 v234, v232, v233
	v_pk_mul_f32 v[236:237], v[24:25], v[36:37]
	v_pk_fma_f32 v[236:237], v[22:23], v[34:35], v[236:237]
	v_add_f32_dpp v234, v234, v234 quad_perm:[1,0,3,2] row_mask:0xf bank_mask:0xf bound_ctrl:1
	s_waitcnt lgkmcnt(5)
	v_pk_mul_f32 v[228:229], v[18:19], v[34:35]
	v_add_f32_e32 v238, v236, v237
	v_add_f32_dpp v234, v234, v234 quad_perm:[2,3,0,1] row_mask:0xf bank_mask:0xf bound_ctrl:1
	v_pk_mul_f32 v[230:231], v[20:21], v[36:37]
	v_pk_fma_f32 v[56:57], v[14:15], v[240:241], v[228:229] op_sel_hi:[1,0,1]
	v_add_f32_dpp v234, v234, v234 row_half_mirror row_mask:0xf bank_mask:0xf bound_ctrl:1
	v_pk_fma_f32 v[54:55], v[16:17], v[240:241], v[230:231] op_sel_hi:[1,0,1]
	v_add_f32_dpp v238, v238, v238 quad_perm:[1,0,3,2] row_mask:0xf bank_mask:0xf bound_ctrl:1
	v_add_f32_dpp v234, v234, v234 row_mirror row_mask:0xf bank_mask:0xf bound_ctrl:1
	ds_read_b32 v242, v62 offset:16640
	ds_read_b128 v[30:33], v51 offset:16384
	ds_read_b128 v[22:25], v51 offset:15360
	s_waitcnt lgkmcnt(6)
	v_pk_fma_f32 v[36:37], v[12:13], v[234:235], v[54:55] op_sel_hi:[1,0,1]
	v_pk_fma_f32 v[34:35], v[10:11], v[234:235], v[56:57] op_sel_hi:[1,0,1]
	v_add_f32_dpp v238, v238, v238 quad_perm:[2,3,0,1] row_mask:0xf bank_mask:0xf bound_ctrl:1
	ds_write_b32 v49, v238 offset:2048
	ds_read_b128 v[26:29], v51 offset:17664
	s_waitcnt lgkmcnt(5)
	v_pk_mul_f32 v[232:233], v[226:227], v[36:37]
	v_pk_fma_f32 v[232:233], v[224:225], v[34:35], v[232:233]
	ds_read_b128 v[18:21], v51 offset:17152
	ds_read_b128 v[14:17], v51 offset:17408
	v_add_f32_e32 v234, v232, v233
	v_pk_mul_f32 v[236:237], v[8:9], v[36:37]
	v_pk_fma_f32 v[236:237], v[6:7], v[34:35], v[236:237]
	v_add_f32_dpp v234, v234, v234 quad_perm:[1,0,3,2] row_mask:0xf bank_mask:0xf bound_ctrl:1
	s_waitcnt lgkmcnt(5)
	v_pk_mul_f32 v[228:229], v[64:65], v[34:35]
	v_add_f32_e32 v238, v236, v237
	v_add_f32_dpp v234, v234, v234 quad_perm:[2,3,0,1] row_mask:0xf bank_mask:0xf bound_ctrl:1
	v_pk_mul_f32 v[230:231], v[66:67], v[36:37]
	v_pk_fma_f32 v[56:57], v[68:69], v[242:243], v[228:229] op_sel_hi:[1,0,1]
	v_add_f32_dpp v234, v234, v234 row_half_mirror row_mask:0xf bank_mask:0xf bound_ctrl:1
	v_pk_fma_f32 v[54:55], v[70:71], v[242:243], v[230:231] op_sel_hi:[1,0,1]
	v_add_f32_dpp v238, v238, v238 quad_perm:[1,0,3,2] row_mask:0xf bank_mask:0xf bound_ctrl:1
	v_add_f32_dpp v234, v234, v234 row_mirror row_mask:0xf bank_mask:0xf bound_ctrl:1
	ds_read_b32 v240, v62 offset:18176
	ds_read_b128 v[10:13], v51 offset:17920
	ds_read_b128 v[6:9], v51 offset:16896
	s_waitcnt lgkmcnt(6)
	v_pk_fma_f32 v[36:37], v[32:33], v[234:235], v[54:55] op_sel_hi:[1,0,1]
	v_pk_fma_f32 v[34:35], v[30:31], v[234:235], v[56:57] op_sel_hi:[1,0,1]
	v_add_f32_dpp v238, v238, v238 quad_perm:[2,3,0,1] row_mask:0xf bank_mask:0xf bound_ctrl:1
	ds_write_b32 v49, v238 offset:2304
	ds_read_b128 v[224:227], v51 offset:19200
	s_waitcnt lgkmcnt(5)
	v_pk_mul_f32 v[232:233], v[28:29], v[36:37]
	v_pk_fma_f32 v[232:233], v[26:27], v[34:35], v[232:233]
	ds_read_b128 v[64:67], v51 offset:18688
	ds_read_b128 v[68:71], v51 offset:18944
	v_add_f32_e32 v234, v232, v233
	v_pk_mul_f32 v[236:237], v[24:25], v[36:37]
	v_pk_fma_f32 v[236:237], v[22:23], v[34:35], v[236:237]
	v_add_f32_dpp v234, v234, v234 quad_perm:[1,0,3,2] row_mask:0xf bank_mask:0xf bound_ctrl:1
	s_waitcnt lgkmcnt(5)
	v_pk_mul_f32 v[228:229], v[18:19], v[34:35]
	v_add_f32_e32 v238, v236, v237
	v_add_f32_dpp v234, v234, v234 quad_perm:[2,3,0,1] row_mask:0xf bank_mask:0xf bound_ctrl:1
	v_pk_mul_f32 v[230:231], v[20:21], v[36:37]
	v_pk_fma_f32 v[56:57], v[14:15], v[240:241], v[228:229] op_sel_hi:[1,0,1]
	v_add_f32_dpp v234, v234, v234 row_half_mirror row_mask:0xf bank_mask:0xf bound_ctrl:1
	v_pk_fma_f32 v[54:55], v[16:17], v[240:241], v[230:231] op_sel_hi:[1,0,1]
	v_add_f32_dpp v238, v238, v238 quad_perm:[1,0,3,2] row_mask:0xf bank_mask:0xf bound_ctrl:1
	v_add_f32_dpp v234, v234, v234 row_mirror row_mask:0xf bank_mask:0xf bound_ctrl:1
	ds_read_b32 v242, v62 offset:19712
	ds_read_b128 v[30:33], v51 offset:19456
	ds_read_b128 v[22:25], v51 offset:18432
	s_waitcnt lgkmcnt(6)
	v_pk_fma_f32 v[36:37], v[12:13], v[234:235], v[54:55] op_sel_hi:[1,0,1]
	v_pk_fma_f32 v[34:35], v[10:11], v[234:235], v[56:57] op_sel_hi:[1,0,1]
	v_add_f32_dpp v238, v238, v238 quad_perm:[2,3,0,1] row_mask:0xf bank_mask:0xf bound_ctrl:1
	ds_write_b32 v49, v238 offset:2560
	ds_read_b128 v[26:29], v51 offset:20736
	s_waitcnt lgkmcnt(5)
	v_pk_mul_f32 v[232:233], v[226:227], v[36:37]
	v_pk_fma_f32 v[232:233], v[224:225], v[34:35], v[232:233]
	ds_read_b128 v[18:21], v51 offset:20224
	ds_read_b128 v[14:17], v51 offset:20480
	v_add_f32_e32 v234, v232, v233
	v_pk_mul_f32 v[236:237], v[8:9], v[36:37]
	v_pk_fma_f32 v[236:237], v[6:7], v[34:35], v[236:237]
	v_add_f32_dpp v234, v234, v234 quad_perm:[1,0,3,2] row_mask:0xf bank_mask:0xf bound_ctrl:1
	s_waitcnt lgkmcnt(5)
	v_pk_mul_f32 v[228:229], v[64:65], v[34:35]
	v_add_f32_e32 v238, v236, v237
	v_add_f32_dpp v234, v234, v234 quad_perm:[2,3,0,1] row_mask:0xf bank_mask:0xf bound_ctrl:1
	v_pk_mul_f32 v[230:231], v[66:67], v[36:37]
	v_pk_fma_f32 v[56:57], v[68:69], v[242:243], v[228:229] op_sel_hi:[1,0,1]
	v_add_f32_dpp v234, v234, v234 row_half_mirror row_mask:0xf bank_mask:0xf bound_ctrl:1
	v_pk_fma_f32 v[54:55], v[70:71], v[242:243], v[230:231] op_sel_hi:[1,0,1]
	v_add_f32_dpp v238, v238, v238 quad_perm:[1,0,3,2] row_mask:0xf bank_mask:0xf bound_ctrl:1
	v_add_f32_dpp v234, v234, v234 row_mirror row_mask:0xf bank_mask:0xf bound_ctrl:1
	ds_read_b32 v240, v62 offset:21248
	ds_read_b128 v[10:13], v51 offset:20992
	ds_read_b128 v[6:9], v51 offset:19968
	s_waitcnt lgkmcnt(6)
	v_pk_fma_f32 v[36:37], v[32:33], v[234:235], v[54:55] op_sel_hi:[1,0,1]
	v_pk_fma_f32 v[34:35], v[30:31], v[234:235], v[56:57] op_sel_hi:[1,0,1]
	v_add_f32_dpp v238, v238, v238 quad_perm:[2,3,0,1] row_mask:0xf bank_mask:0xf bound_ctrl:1
	ds_write_b32 v49, v238 offset:2816
	ds_read_b128 v[224:227], v51 offset:22272
	s_waitcnt lgkmcnt(5)
	v_pk_mul_f32 v[232:233], v[28:29], v[36:37]
	v_pk_fma_f32 v[232:233], v[26:27], v[34:35], v[232:233]
	ds_read_b128 v[64:67], v51 offset:21760
	ds_read_b128 v[68:71], v51 offset:22016
	v_add_f32_e32 v234, v232, v233
	v_pk_mul_f32 v[236:237], v[24:25], v[36:37]
	v_pk_fma_f32 v[236:237], v[22:23], v[34:35], v[236:237]
	v_add_f32_dpp v234, v234, v234 quad_perm:[1,0,3,2] row_mask:0xf bank_mask:0xf bound_ctrl:1
	s_waitcnt lgkmcnt(5)
	v_pk_mul_f32 v[228:229], v[18:19], v[34:35]
	v_add_f32_e32 v238, v236, v237
	v_add_f32_dpp v234, v234, v234 quad_perm:[2,3,0,1] row_mask:0xf bank_mask:0xf bound_ctrl:1
	v_pk_mul_f32 v[230:231], v[20:21], v[36:37]
	v_pk_fma_f32 v[56:57], v[14:15], v[240:241], v[228:229] op_sel_hi:[1,0,1]
	v_add_f32_dpp v234, v234, v234 row_half_mirror row_mask:0xf bank_mask:0xf bound_ctrl:1
	v_pk_fma_f32 v[54:55], v[16:17], v[240:241], v[230:231] op_sel_hi:[1,0,1]
	v_add_f32_dpp v238, v238, v238 quad_perm:[1,0,3,2] row_mask:0xf bank_mask:0xf bound_ctrl:1
	v_add_f32_dpp v234, v234, v234 row_mirror row_mask:0xf bank_mask:0xf bound_ctrl:1
	ds_read_b32 v242, v62 offset:22784
	ds_read_b128 v[30:33], v51 offset:22528
	ds_read_b128 v[22:25], v51 offset:21504
	s_waitcnt lgkmcnt(6)
	v_pk_fma_f32 v[36:37], v[12:13], v[234:235], v[54:55] op_sel_hi:[1,0,1]
	v_pk_fma_f32 v[34:35], v[10:11], v[234:235], v[56:57] op_sel_hi:[1,0,1]
	v_add_f32_dpp v238, v238, v238 quad_perm:[2,3,0,1] row_mask:0xf bank_mask:0xf bound_ctrl:1
	ds_write_b32 v49, v238 offset:3072
	ds_read_b128 v[26:29], v51 offset:23808
	s_waitcnt lgkmcnt(5)
	v_pk_mul_f32 v[232:233], v[226:227], v[36:37]
	v_pk_fma_f32 v[232:233], v[224:225], v[34:35], v[232:233]
	ds_read_b128 v[18:21], v51 offset:23296
	ds_read_b128 v[14:17], v51 offset:23552
	v_add_f32_e32 v234, v232, v233
	v_pk_mul_f32 v[236:237], v[8:9], v[36:37]
	v_pk_fma_f32 v[236:237], v[6:7], v[34:35], v[236:237]
	v_add_f32_dpp v234, v234, v234 quad_perm:[1,0,3,2] row_mask:0xf bank_mask:0xf bound_ctrl:1
	s_waitcnt lgkmcnt(5)
	v_pk_mul_f32 v[228:229], v[64:65], v[34:35]
	v_add_f32_e32 v238, v236, v237
	v_add_f32_dpp v234, v234, v234 quad_perm:[2,3,0,1] row_mask:0xf bank_mask:0xf bound_ctrl:1
	v_pk_mul_f32 v[230:231], v[66:67], v[36:37]
	v_pk_fma_f32 v[56:57], v[68:69], v[242:243], v[228:229] op_sel_hi:[1,0,1]
	v_add_f32_dpp v234, v234, v234 row_half_mirror row_mask:0xf bank_mask:0xf bound_ctrl:1
	v_pk_fma_f32 v[54:55], v[70:71], v[242:243], v[230:231] op_sel_hi:[1,0,1]
	v_add_f32_dpp v238, v238, v238 quad_perm:[1,0,3,2] row_mask:0xf bank_mask:0xf bound_ctrl:1
	v_add_f32_dpp v234, v234, v234 row_mirror row_mask:0xf bank_mask:0xf bound_ctrl:1
	ds_read_b32 v240, v62 offset:24320
	ds_read_b128 v[10:13], v51 offset:24064
	ds_read_b128 v[6:9], v51 offset:23040
	s_waitcnt lgkmcnt(6)
	v_pk_fma_f32 v[36:37], v[32:33], v[234:235], v[54:55] op_sel_hi:[1,0,1]
	v_pk_fma_f32 v[34:35], v[30:31], v[234:235], v[56:57] op_sel_hi:[1,0,1]
	v_add_f32_dpp v238, v238, v238 quad_perm:[2,3,0,1] row_mask:0xf bank_mask:0xf bound_ctrl:1
	ds_write_b32 v49, v238 offset:3328
	s_waitcnt lgkmcnt(4)
	v_pk_mul_f32 v[232:233], v[28:29], v[36:37]
	v_pk_fma_f32 v[232:233], v[26:27], v[34:35], v[232:233]
	v_add_f32_e32 v234, v232, v233
	v_pk_mul_f32 v[236:237], v[24:25], v[36:37]
	v_pk_fma_f32 v[236:237], v[22:23], v[34:35], v[236:237]
	v_add_f32_dpp v234, v234, v234 quad_perm:[1,0,3,2] row_mask:0xf bank_mask:0xf bound_ctrl:1
	s_waitcnt lgkmcnt(2)
	v_pk_mul_f32 v[228:229], v[18:19], v[34:35]
	v_add_f32_e32 v238, v236, v237
	v_add_f32_dpp v234, v234, v234 quad_perm:[2,3,0,1] row_mask:0xf bank_mask:0xf bound_ctrl:1
	v_pk_mul_f32 v[230:231], v[20:21], v[36:37]
	v_pk_fma_f32 v[56:57], v[14:15], v[240:241], v[228:229] op_sel_hi:[1,0,1]
	v_add_f32_dpp v234, v234, v234 row_half_mirror row_mask:0xf bank_mask:0xf bound_ctrl:1
	v_pk_fma_f32 v[54:55], v[16:17], v[240:241], v[230:231] op_sel_hi:[1,0,1]
	v_add_f32_dpp v238, v238, v238 quad_perm:[1,0,3,2] row_mask:0xf bank_mask:0xf bound_ctrl:1
	v_add_f32_dpp v234, v234, v234 row_mirror row_mask:0xf bank_mask:0xf bound_ctrl:1
	s_waitcnt lgkmcnt(1)
	v_pk_fma_f32 v[36:37], v[12:13], v[234:235], v[54:55] op_sel_hi:[1,0,1]
	v_pk_fma_f32 v[34:35], v[10:11], v[234:235], v[56:57] op_sel_hi:[1,0,1]
	v_add_f32_dpp v238, v238, v238 quad_perm:[2,3,0,1] row_mask:0xf bank_mask:0xf bound_ctrl:1
	ds_write_b32 v49, v238 offset:3584
	v_pk_mul_f32 v[236:237], v[8:9], v[36:37]
	v_pk_fma_f32 v[236:237], v[6:7], v[34:35], v[236:237]
	v_add_f32_e32 v238, v236, v237
	s_nop 1
	v_add_f32_dpp v52, v238, v238 quad_perm:[1,0,3,2] row_mask:0xf bank_mask:0xf bound_ctrl:1
	s_nop 1
	v_mov_b32_dpp v64, v52 quad_perm:[2,3,0,1] row_mask:0xf bank_mask:0xf bound_ctrl:1
